# LN1/LN2 epilogue: final X (fp32) and H (bf16) row stores made write-through (sc1) so the L2 write-back at the grid barrier has less to flush
# speedup vs baseline: 1.0282x; 1.0054x over previous
.Lln1_pok1:
	v_add_f32_e32 v250, v250, v226
	v_add_f32_e32 v252, v252, v228
	v_add_f32_e32 v250, v250, v230
	v_add_f32_e32 v252, v252, v232
	v_add_f32_e32 v250, v250, v234
	v_add_f32_e32 v252, v252, v236
	v_add_f32_e32 v250, v250, v238
	v_add_f32_e32 v252, v252, v240
	v_add_f32_e32 v250, v250, v206
	v_add_f32_e32 v252, v252, v208
	v_add_f32_e32 v250, v250, v210
	v_add_f32_e32 v252, v252, v212
	v_add_f32_e32 v250, v250, v214
	v_add_f32_e32 v252, v252, v216
	v_add_f32_e32 v250, v250, v218
	v_add_f32_e32 v252, v252, v220
	global_load_dwordx4 v[226:229], v246, s[22:23]
	global_load_dwordx4 v[230:233], v246, s[22:23] offset:64
	global_load_dwordx4 v[234:237], v246, s[22:23] offset:128
	global_load_dwordx4 v[238:241], v246, s[22:23] offset:192
	v_mov_b32_e32 v206, v250
	v_mov_b32_e32 v207, v252
	v_mul_f32_e32 v208, 0x3a800000, v206
	v_mul_f32_e32 v209, v208, v208
	v_mov_b32_e32 v216, 0x3a800000
	v_fma_f32 v209, v207, v216, -v209
	v_max_f32_e32 v209, 0, v209
	v_add_f32_e32 v209, 0x3727c5ac, v209
	v_rsq_f32_e32 v209, v209
	v_mov_b32_e32 v210, v208
	v_mov_b32_e32 v211, v208
	v_mov_b32_e32 v214, v209
	v_mov_b32_e32 v215, v209
	s_nop 1
	v_permlane16_swap_b32_e32 v210, v211
	v_permlane16_swap_b32_e32 v214, v215
	v_mov_b32_e32 v212, v210
	v_mov_b32_e32 v213, v211
	v_mov_b32_e32 v216, v214
	v_mov_b32_e32 v217, v215
	s_nop 1
	v_permlane32_swap_b32_e32 v210, v212
	v_permlane32_swap_b32_e32 v211, v213
	v_permlane32_swap_b32_e32 v214, v216
	v_permlane32_swap_b32_e32 v215, v217
	v_readfirstlane_b32 s64, v137
	s_lshr_b32 s64, s64, 6
	s_lshl_b32 s64, s64, 14
	v_and_b32_e32 v222, 63, v137
	v_and_b32_e32 v246, 15, v222
	v_lshrrev_b32_e32 v247, 4, v222
	v_and_b32_e32 v248, 3, v246
	v_xor_b32_e32 v248, v248, v247
	v_lshlrev_b32_e32 v248, 4, v248
	v_lshl_add_u32 v248, v246, 8, v248
	v_add_u32_e32 v248, s64, v248
	v_lshl_add_u32 v249, v222, 4, s64
	v_add_u32_e32 v250, s36, v247
	v_lshlrev_b32_e32 v250, 12, v250
	v_xor_b32_e32 v251, v246, v247
	v_lshl_add_u32 v250, v251, 4, v250
	s_lshl_b32 s65, s37, 2
	v_add_u32_e32 v250, s65, v250
	v_sub_f32_e32 v62, v62, v210
	v_sub_f32_e32 v63, v63, v210
	v_sub_f32_e32 v64, v64, v210
	v_sub_f32_e32 v65, v65, v210
	v_mul_f32_e32 v62, v214, v62
	v_mul_f32_e32 v63, v214, v63
	v_mul_f32_e32 v64, v214, v64
	v_mul_f32_e32 v65, v214, v65
	v_fma_f32 v62, v66, v62, v90
	v_fma_f32 v63, v67, v63, v91
	v_fma_f32 v64, v68, v64, v92
	v_fma_f32 v65, v69, v65, v93
	ds_write_b128 v248, v[62:65] offset:0
	v_sub_f32_e32 v86, v86, v210
	v_sub_f32_e32 v87, v87, v210
	v_sub_f32_e32 v88, v88, v210
	v_sub_f32_e32 v89, v89, v210
	v_mul_f32_e32 v86, v214, v86
	v_mul_f32_e32 v87, v214, v87
	v_mul_f32_e32 v88, v214, v88
	v_mul_f32_e32 v89, v214, v89
	v_fma_f32 v86, v74, v86, v94
	v_fma_f32 v87, v75, v87, v95
	v_fma_f32 v88, v76, v88, v96
	v_fma_f32 v89, v77, v89, v97
	ds_write_b128 v248, v[86:89] offset:64
	v_sub_f32_e32 v70, v70, v210
	v_sub_f32_e32 v71, v71, v210
	v_sub_f32_e32 v72, v72, v210
	v_sub_f32_e32 v73, v73, v210
	v_mul_f32_e32 v70, v214, v70
	v_mul_f32_e32 v71, v214, v71
	v_mul_f32_e32 v72, v214, v72
	v_mul_f32_e32 v73, v214, v73
	v_fma_f32 v70, v78, v70, v108
	v_fma_f32 v71, v79, v71, v109
	v_fma_f32 v72, v80, v72, v110
	v_fma_f32 v73, v81, v73, v111
	ds_write_b128 v248, v[70:73] offset:128
	v_sub_f32_e32 v176, v176, v210
	v_sub_f32_e32 v177, v177, v210
	v_sub_f32_e32 v178, v178, v210
	v_sub_f32_e32 v179, v179, v210
	v_mul_f32_e32 v176, v214, v176
	v_mul_f32_e32 v177, v214, v177
	v_mul_f32_e32 v178, v214, v178
	v_mul_f32_e32 v179, v214, v179
	v_fma_f32 v176, v82, v176, v172
	v_fma_f32 v177, v83, v177, v173
	v_fma_f32 v178, v84, v178, v174
	v_fma_f32 v179, v85, v179, v175
	ds_write_b128 v248, v[176:179] offset:192
	v_sub_f32_e32 v202, v202, v211
	v_sub_f32_e32 v203, v203, v211
	v_sub_f32_e32 v204, v204, v211
	v_sub_f32_e32 v205, v205, v211
	v_mul_f32_e32 v202, v215, v202
	v_mul_f32_e32 v203, v215, v203
	v_mul_f32_e32 v204, v215, v204
	v_mul_f32_e32 v205, v215, v205
	v_fma_f32 v202, v66, v202, v90
	v_fma_f32 v203, v67, v203, v91
	v_fma_f32 v204, v68, v204, v92
	v_fma_f32 v205, v69, v205, v93
	ds_write_b128 v248, v[202:205] offset:4096
	v_sub_f32_e32 v54, v54, v211
	v_sub_f32_e32 v55, v55, v211
	v_sub_f32_e32 v56, v56, v211
	v_sub_f32_e32 v57, v57, v211
	v_mul_f32_e32 v54, v215, v54
	v_mul_f32_e32 v55, v215, v55
	v_mul_f32_e32 v56, v215, v56
	v_mul_f32_e32 v57, v215, v57
	v_fma_f32 v54, v74, v54, v94
	v_fma_f32 v55, v75, v55, v95
	v_fma_f32 v56, v76, v56, v96
	v_fma_f32 v57, v77, v57, v97
	ds_write_b128 v248, v[54:57] offset:4160
	v_sub_f32_e32 v58, v58, v211
	v_sub_f32_e32 v59, v59, v211
	v_sub_f32_e32 v60, v60, v211
	v_sub_f32_e32 v61, v61, v211
	v_mul_f32_e32 v58, v215, v58
	v_mul_f32_e32 v59, v215, v59
	v_mul_f32_e32 v60, v215, v60
	v_mul_f32_e32 v61, v215, v61
	v_fma_f32 v58, v78, v58, v108
	v_fma_f32 v59, v79, v59, v109
	v_fma_f32 v60, v80, v60, v110
	v_fma_f32 v61, v81, v61, v111
	ds_write_b128 v248, v[58:61] offset:4224
	v_sub_f32_e32 v34, v34, v211
	v_sub_f32_e32 v35, v35, v211
	v_sub_f32_e32 v36, v36, v211
	v_sub_f32_e32 v37, v37, v211
	v_mul_f32_e32 v34, v215, v34
	v_mul_f32_e32 v35, v215, v35
	v_mul_f32_e32 v36, v215, v36
	v_mul_f32_e32 v37, v215, v37
	v_fma_f32 v34, v82, v34, v172
	v_fma_f32 v35, v83, v35, v173
	v_fma_f32 v36, v84, v36, v174
	v_fma_f32 v37, v85, v37, v175
	ds_write_b128 v248, v[34:37] offset:4288
	v_sub_f32_e32 v30, v30, v212
	v_sub_f32_e32 v31, v31, v212
	v_sub_f32_e32 v32, v32, v212
	v_sub_f32_e32 v33, v33, v212
	v_mul_f32_e32 v30, v216, v30
	v_mul_f32_e32 v31, v216, v31
	v_mul_f32_e32 v32, v216, v32
	v_mul_f32_e32 v33, v216, v33
	v_fma_f32 v30, v66, v30, v90
	v_fma_f32 v31, v67, v31, v91
	v_fma_f32 v32, v68, v32, v92
	v_fma_f32 v33, v69, v33, v93
	ds_write_b128 v248, v[30:33] offset:8192
	v_sub_f32_e32 v26, v26, v212
	v_sub_f32_e32 v27, v27, v212
	v_sub_f32_e32 v28, v28, v212
	v_sub_f32_e32 v29, v29, v212
	v_mul_f32_e32 v26, v216, v26
	v_mul_f32_e32 v27, v216, v27
	v_mul_f32_e32 v28, v216, v28
	v_mul_f32_e32 v29, v216, v29
	v_fma_f32 v26, v74, v26, v94
	v_fma_f32 v27, v75, v27, v95
	v_fma_f32 v28, v76, v28, v96
	v_fma_f32 v29, v77, v29, v97
	ds_write_b128 v248, v[26:29] offset:8256
	v_sub_f32_e32 v22, v22, v212
	v_sub_f32_e32 v23, v23, v212
	v_sub_f32_e32 v24, v24, v212
	v_sub_f32_e32 v25, v25, v212
	v_mul_f32_e32 v22, v216, v22
	v_mul_f32_e32 v23, v216, v23
	v_mul_f32_e32 v24, v216, v24
	v_mul_f32_e32 v25, v216, v25
	v_fma_f32 v22, v78, v22, v108
	v_fma_f32 v23, v79, v23, v109
	v_fma_f32 v24, v80, v24, v110
	v_fma_f32 v25, v81, v25, v111
	ds_write_b128 v248, v[22:25] offset:8320
	v_sub_f32_e32 v18, v18, v212
	v_sub_f32_e32 v19, v19, v212
	v_sub_f32_e32 v20, v20, v212
	v_sub_f32_e32 v21, v21, v212
	v_mul_f32_e32 v18, v216, v18
	v_mul_f32_e32 v19, v216, v19
	v_mul_f32_e32 v20, v216, v20
	v_mul_f32_e32 v21, v216, v21
	v_fma_f32 v18, v82, v18, v172
	v_fma_f32 v19, v83, v19, v173
	v_fma_f32 v20, v84, v20, v174
	v_fma_f32 v21, v85, v21, v175
	ds_write_b128 v248, v[18:21] offset:8384
	v_sub_f32_e32 v14, v14, v213
	v_sub_f32_e32 v15, v15, v213
	v_sub_f32_e32 v16, v16, v213
	v_sub_f32_e32 v17, v17, v213
	v_mul_f32_e32 v14, v217, v14
	v_mul_f32_e32 v15, v217, v15
	v_mul_f32_e32 v16, v217, v16
	v_mul_f32_e32 v17, v217, v17
	v_fma_f32 v14, v66, v14, v90
	v_fma_f32 v15, v67, v15, v91
	v_fma_f32 v16, v68, v16, v92
	v_fma_f32 v17, v69, v17, v93
	ds_write_b128 v248, v[14:17] offset:12288
	v_sub_f32_e32 v10, v10, v213
	v_sub_f32_e32 v11, v11, v213
	v_sub_f32_e32 v12, v12, v213
	v_sub_f32_e32 v13, v13, v213
	v_mul_f32_e32 v10, v217, v10
	v_mul_f32_e32 v11, v217, v11
	v_mul_f32_e32 v12, v217, v12
	v_mul_f32_e32 v13, v217, v13
	v_fma_f32 v10, v74, v10, v94
	v_fma_f32 v11, v75, v11, v95
	v_fma_f32 v12, v76, v12, v96
	v_fma_f32 v13, v77, v13, v97
	ds_write_b128 v248, v[10:13] offset:12352
	v_sub_f32_e32 v6, v6, v213
	v_sub_f32_e32 v7, v7, v213
	v_sub_f32_e32 v8, v8, v213
	v_sub_f32_e32 v9, v9, v213
	v_mul_f32_e32 v6, v217, v6
	v_mul_f32_e32 v7, v217, v7
	v_mul_f32_e32 v8, v217, v8
	v_mul_f32_e32 v9, v217, v9
	v_fma_f32 v6, v78, v6, v108
	v_fma_f32 v7, v79, v7, v109
	v_fma_f32 v8, v80, v8, v110
	v_fma_f32 v9, v81, v9, v111
	ds_write_b128 v248, v[6:9] offset:12416
	v_sub_f32_e32 v2, v2, v213
	v_sub_f32_e32 v3, v3, v213
	v_sub_f32_e32 v4, v4, v213
	v_sub_f32_e32 v5, v5, v213
	v_mul_f32_e32 v2, v217, v2
	v_mul_f32_e32 v3, v217, v3
	v_mul_f32_e32 v4, v217, v4
	v_mul_f32_e32 v5, v217, v5
	v_fma_f32 v2, v82, v2, v172
	v_fma_f32 v3, v83, v3, v173
	v_fma_f32 v4, v84, v4, v174
	v_fma_f32 v5, v85, v5, v175
	ds_write_b128 v248, v[2:5] offset:12480
	s_waitcnt lgkmcnt(0)
	ds_read_b128 v[66:69], v249 offset:0
	ds_read_b128 v[74:77], v249 offset:1024
	ds_read_b128 v[78:81], v249 offset:2048
	ds_read_b128 v[82:85], v249 offset:3072
	ds_read_b128 v[90:93], v249 offset:4096
	ds_read_b128 v[94:97], v249 offset:5120
	ds_read_b128 v[108:111], v249 offset:6144
	ds_read_b128 v[172:175], v249 offset:7168
	s_waitcnt lgkmcnt(7)
	global_store_dwordx4 v250, v[66:69], s[26:27] sc1
	s_waitcnt lgkmcnt(6)
	v_add_u32_e32 v251, 0x4000, v250
	global_store_dwordx4 v251, v[74:77], s[26:27] sc1
	s_waitcnt lgkmcnt(5)
	v_add_u32_e32 v251, 0x8000, v250
	global_store_dwordx4 v251, v[78:81], s[26:27] sc1
	s_waitcnt lgkmcnt(4)
	v_add_u32_e32 v251, 0xc000, v250
	global_store_dwordx4 v251, v[82:85], s[26:27] sc1
	s_waitcnt lgkmcnt(3)
	v_add_u32_e32 v251, 0x10000, v250
	global_store_dwordx4 v251, v[90:93], s[26:27] sc1
	s_waitcnt lgkmcnt(2)
	v_add_u32_e32 v251, 0x14000, v250
	global_store_dwordx4 v251, v[94:97], s[26:27] sc1
	s_waitcnt lgkmcnt(1)
	v_add_u32_e32 v251, 0x18000, v250
	global_store_dwordx4 v251, v[108:111], s[26:27] sc1
	s_waitcnt lgkmcnt(0)
	v_add_u32_e32 v251, 0x1c000, v250
	global_store_dwordx4 v251, v[172:175], s[26:27] sc1
	s_nop 1
	ds_read_b128 v[66:69], v249 offset:8192
	ds_read_b128 v[74:77], v249 offset:9216
	ds_read_b128 v[78:81], v249 offset:10240
	ds_read_b128 v[82:85], v249 offset:11264
	ds_read_b128 v[90:93], v249 offset:12288
	ds_read_b128 v[94:97], v249 offset:13312
	ds_read_b128 v[108:111], v249 offset:14336
	ds_read_b128 v[172:175], v249 offset:15360
	s_waitcnt lgkmcnt(7)
	v_add_u32_e32 v251, 0x20000, v250
	global_store_dwordx4 v251, v[66:69], s[26:27] sc1
	s_waitcnt lgkmcnt(6)
	v_add_u32_e32 v251, 0x24000, v250
	global_store_dwordx4 v251, v[74:77], s[26:27] sc1
	s_waitcnt lgkmcnt(5)
	v_add_u32_e32 v251, 0x28000, v250
	global_store_dwordx4 v251, v[78:81], s[26:27] sc1
	s_waitcnt lgkmcnt(4)
	v_add_u32_e32 v251, 0x2c000, v250
	global_store_dwordx4 v251, v[82:85], s[26:27] sc1
	s_waitcnt lgkmcnt(3)
	v_add_u32_e32 v251, 0x30000, v250
	global_store_dwordx4 v251, v[90:93], s[26:27] sc1
	s_waitcnt lgkmcnt(2)
	v_add_u32_e32 v251, 0x34000, v250
	global_store_dwordx4 v251, v[94:97], s[26:27] sc1
	s_waitcnt lgkmcnt(1)
	v_add_u32_e32 v251, 0x38000, v250
	global_store_dwordx4 v251, v[108:111], s[26:27] sc1
	s_waitcnt lgkmcnt(0)
	v_add_u32_e32 v251, 0x3c000, v250
	global_store_dwordx4 v251, v[172:175], s[26:27] sc1
	s_nop 1
	s_add_u32 s44, s94, 0x7b48000
	s_addc_u32 s45, s95, 0
	s_waitcnt vmcnt(16)
	v_add_f32_e32 v226, 1.0, v226
	v_add_f32_e32 v227, 1.0, v227
	v_add_f32_e32 v228, 1.0, v228
	v_add_f32_e32 v229, 1.0, v229
	v_add_f32_e32 v230, 1.0, v230
	v_add_f32_e32 v231, 1.0, v231
	v_add_f32_e32 v232, 1.0, v232
	v_add_f32_e32 v233, 1.0, v233
	v_add_f32_e32 v234, 1.0, v234
	v_add_f32_e32 v235, 1.0, v235
	v_add_f32_e32 v236, 1.0, v236
	v_add_f32_e32 v237, 1.0, v237
	v_add_f32_e32 v238, 1.0, v238
	v_add_f32_e32 v239, 1.0, v239
	v_add_f32_e32 v240, 1.0, v240
	v_add_f32_e32 v241, 1.0, v241
	v_and_b32_e32 v251, 7, v246
	v_lshlrev_b32_e32 v251, 1, v251
	v_or_b32_e32 v218, 0, v247
	v_xor_b32_e32 v218, v218, v251
	v_lshlrev_b32_e32 v218, 3, v218
	v_lshl_add_u32 v218, v246, 7, v218
	v_add_u32_e32 v218, s64, v218
	v_or_b32_e32 v219, 4, v247
	v_xor_b32_e32 v219, v219, v251
	v_lshlrev_b32_e32 v219, 3, v219
	v_lshl_add_u32 v219, v246, 7, v219
	v_add_u32_e32 v219, s64, v219
	v_or_b32_e32 v220, 8, v247
	v_xor_b32_e32 v220, v220, v251
	v_lshlrev_b32_e32 v220, 3, v220
	v_lshl_add_u32 v220, v246, 7, v220
	v_add_u32_e32 v220, s64, v220
	v_or_b32_e32 v221, 12, v247
	v_xor_b32_e32 v221, v221, v251
	v_lshlrev_b32_e32 v221, 3, v221
	v_lshl_add_u32 v221, v246, 7, v221
	v_add_u32_e32 v221, s64, v221
	v_lshrrev_b32_e32 v248, 3, v222
	v_and_b32_e32 v251, 7, v222
	v_xor_b32_e32 v251, v251, v248
	v_add_u32_e32 v248, s36, v248
	v_lshlrev_b32_e32 v248, 11, v248
	v_lshl_add_u32 v248, v251, 4, v248
	s_lshl_b32 s65, s37, 1
	v_add_u32_e32 v248, s65, v248
	v_fma_f32 v62, v226, v62, v38
	v_fma_f32 v63, v227, v63, v39
	v_fma_f32 v64, v228, v64, v40
	v_fma_f32 v65, v229, v65, v41
	v_cvt_pk_bf16_f32 v62, v62, v63
	v_cvt_pk_bf16_f32 v63, v64, v65
	ds_write_b64 v218, v[62:63] offset:0
	v_fma_f32 v86, v230, v86, v42
	v_fma_f32 v87, v231, v87, v43
	v_fma_f32 v88, v232, v88, v44
	v_fma_f32 v89, v233, v89, v45
	v_cvt_pk_bf16_f32 v86, v86, v87
	v_cvt_pk_bf16_f32 v87, v88, v89
	ds_write_b64 v219, v[86:87] offset:0
	v_fma_f32 v70, v234, v70, v46
	v_fma_f32 v71, v235, v71, v47
	v_fma_f32 v72, v236, v72, v48
	v_fma_f32 v73, v237, v73, v49
	v_cvt_pk_bf16_f32 v70, v70, v71
	v_cvt_pk_bf16_f32 v71, v72, v73
	ds_write_b64 v220, v[70:71] offset:0
	v_fma_f32 v176, v238, v176, v50
	v_fma_f32 v177, v239, v177, v51
	v_fma_f32 v178, v240, v178, v52
	v_fma_f32 v179, v241, v179, v53
	v_cvt_pk_bf16_f32 v176, v176, v177
	v_cvt_pk_bf16_f32 v177, v178, v179
	ds_write_b64 v221, v[176:177] offset:0
	v_fma_f32 v202, v226, v202, v38
	v_fma_f32 v203, v227, v203, v39
	v_fma_f32 v204, v228, v204, v40
	v_fma_f32 v205, v229, v205, v41
	v_cvt_pk_bf16_f32 v202, v202, v203
	v_cvt_pk_bf16_f32 v203, v204, v205
	ds_write_b64 v218, v[202:203] offset:2048
	v_fma_f32 v54, v230, v54, v42
	v_fma_f32 v55, v231, v55, v43
	v_fma_f32 v56, v232, v56, v44
	v_fma_f32 v57, v233, v57, v45
	v_cvt_pk_bf16_f32 v54, v54, v55
	v_cvt_pk_bf16_f32 v55, v56, v57
	ds_write_b64 v219, v[54:55] offset:2048
	v_fma_f32 v58, v234, v58, v46
	v_fma_f32 v59, v235, v59, v47
	v_fma_f32 v60, v236, v60, v48
	v_fma_f32 v61, v237, v61, v49
	v_cvt_pk_bf16_f32 v58, v58, v59
	v_cvt_pk_bf16_f32 v59, v60, v61
	ds_write_b64 v220, v[58:59] offset:2048
	v_fma_f32 v34, v238, v34, v50
	v_fma_f32 v35, v239, v35, v51
	v_fma_f32 v36, v240, v36, v52
	v_fma_f32 v37, v241, v37, v53
	v_cvt_pk_bf16_f32 v34, v34, v35
	v_cvt_pk_bf16_f32 v35, v36, v37
	ds_write_b64 v221, v[34:35] offset:2048
	v_fma_f32 v30, v226, v30, v38
	v_fma_f32 v31, v227, v31, v39
	v_fma_f32 v32, v228, v32, v40
	v_fma_f32 v33, v229, v33, v41
	v_cvt_pk_bf16_f32 v30, v30, v31
	v_cvt_pk_bf16_f32 v31, v32, v33
	ds_write_b64 v218, v[30:31] offset:4096
	v_fma_f32 v26, v230, v26, v42
	v_fma_f32 v27, v231, v27, v43
	v_fma_f32 v28, v232, v28, v44
	v_fma_f32 v29, v233, v29, v45
	v_cvt_pk_bf16_f32 v26, v26, v27
	v_cvt_pk_bf16_f32 v27, v28, v29
	ds_write_b64 v219, v[26:27] offset:4096
	v_fma_f32 v22, v234, v22, v46
	v_fma_f32 v23, v235, v23, v47
	v_fma_f32 v24, v236, v24, v48
	v_fma_f32 v25, v237, v25, v49
	v_cvt_pk_bf16_f32 v22, v22, v23
	v_cvt_pk_bf16_f32 v23, v24, v25
	ds_write_b64 v220, v[22:23] offset:4096
	v_fma_f32 v18, v238, v18, v50
	v_fma_f32 v19, v239, v19, v51
	v_fma_f32 v20, v240, v20, v52
	v_fma_f32 v21, v241, v21, v53
	v_cvt_pk_bf16_f32 v18, v18, v19
	v_cvt_pk_bf16_f32 v19, v20, v21
	ds_write_b64 v221, v[18:19] offset:4096
	v_fma_f32 v14, v226, v14, v38
	v_fma_f32 v15, v227, v15, v39
	v_fma_f32 v16, v228, v16, v40
	v_fma_f32 v17, v229, v17, v41
	v_cvt_pk_bf16_f32 v14, v14, v15
	v_cvt_pk_bf16_f32 v15, v16, v17
	ds_write_b64 v218, v[14:15] offset:6144
	v_fma_f32 v10, v230, v10, v42
	v_fma_f32 v11, v231, v11, v43
	v_fma_f32 v12, v232, v12, v44
	v_fma_f32 v13, v233, v13, v45
	v_cvt_pk_bf16_f32 v10, v10, v11
	v_cvt_pk_bf16_f32 v11, v12, v13
	ds_write_b64 v219, v[10:11] offset:6144
	v_fma_f32 v6, v234, v6, v46
	v_fma_f32 v7, v235, v7, v47
	v_fma_f32 v8, v236, v8, v48
	v_fma_f32 v9, v237, v9, v49
	v_cvt_pk_bf16_f32 v6, v6, v7
	v_cvt_pk_bf16_f32 v7, v8, v9
	ds_write_b64 v220, v[6:7] offset:6144
	v_fma_f32 v2, v238, v2, v50
	v_fma_f32 v3, v239, v3, v51
	v_fma_f32 v4, v240, v4, v52
	v_fma_f32 v5, v241, v5, v53
	v_cvt_pk_bf16_f32 v2, v2, v3
	v_cvt_pk_bf16_f32 v3, v4, v5
	ds_write_b64 v221, v[2:3] offset:6144
	s_waitcnt lgkmcnt(0)
	ds_read_b128 v[66:69], v249 offset:0
	ds_read_b128 v[74:77], v249 offset:1024
	ds_read_b128 v[78:81], v249 offset:2048
	ds_read_b128 v[82:85], v249 offset:3072
	ds_read_b128 v[90:93], v249 offset:4096
	ds_read_b128 v[94:97], v249 offset:5120
	ds_read_b128 v[108:111], v249 offset:6144
	ds_read_b128 v[172:175], v249 offset:7168
	s_waitcnt lgkmcnt(7)
	global_store_dwordx4 v248, v[66:69], s[44:45] sc1
	s_waitcnt lgkmcnt(6)
	v_add_u32_e32 v251, 0x4000, v248
	global_store_dwordx4 v251, v[74:77], s[44:45] sc1
	s_waitcnt lgkmcnt(5)
	v_add_u32_e32 v251, 0x8000, v248
	global_store_dwordx4 v251, v[78:81], s[44:45] sc1
	s_waitcnt lgkmcnt(4)
	v_add_u32_e32 v251, 0xc000, v248
	global_store_dwordx4 v251, v[82:85], s[44:45] sc1
	s_waitcnt lgkmcnt(3)
	v_add_u32_e32 v251, 0x10000, v248
	global_store_dwordx4 v251, v[90:93], s[44:45] sc1
	s_waitcnt lgkmcnt(2)
	v_add_u32_e32 v251, 0x14000, v248
	global_store_dwordx4 v251, v[94:97], s[44:45] sc1
	s_waitcnt lgkmcnt(1)
	v_add_u32_e32 v251, 0x18000, v248
	global_store_dwordx4 v251, v[108:111], s[44:45] sc1
	s_waitcnt lgkmcnt(0)
	v_add_u32_e32 v251, 0x1c000, v248
	global_store_dwordx4 v251, v[172:175], s[44:45] sc1
	v_readlane_b32 s78, v255, 33
	v_readlane_b32 s79, v255, 34
	s_barrier
	s_load_dword s6, s[78:79], 0x0
	s_mov_b64 s[76:77], 0x7b4c180
	s_mov_b64 s[68:69], 0x7b54180
	s_mov_b64 s[74:75], 0x68800
	s_waitcnt lgkmcnt(0)
	s_add_i32 s60, s6, s60
	s_cmpk_gt_i32 s60, 0xbf
	s_cbranch_scc0 .LBB0_93

.Lln2_nomod:
	v_mov_b32_e32 v206, v250
	v_mov_b32_e32 v207, v252
	v_mul_f32_e32 v208, 0x3a800000, v206
	v_mul_f32_e32 v209, v208, v208
	v_mov_b32_e32 v216, 0x3a800000
	v_fma_f32 v209, v207, v216, -v209
	v_max_f32_e32 v209, 0, v209
	v_add_f32_e32 v209, 0x3727c5ac, v209
	v_rsq_f32_e32 v209, v209
	v_mov_b32_e32 v210, v208
	v_mov_b32_e32 v211, v208
	v_mov_b32_e32 v214, v209
	v_mov_b32_e32 v215, v209
	s_nop 1
	v_permlane16_swap_b32_e32 v210, v211
	v_permlane16_swap_b32_e32 v214, v215
	v_mov_b32_e32 v212, v210
	v_mov_b32_e32 v213, v211
	v_mov_b32_e32 v216, v214
	v_mov_b32_e32 v217, v215
	s_nop 1
	v_permlane32_swap_b32_e32 v210, v212
	v_permlane32_swap_b32_e32 v211, v213
	v_permlane32_swap_b32_e32 v214, v216
	v_permlane32_swap_b32_e32 v215, v217
	s_cmp_eq_u32 s53, 3
	s_cselect_b32 s26, s92, s26
	s_cselect_b32 s27, s93, s27
	v_readfirstlane_b32 s54, v137
	s_lshr_b32 s54, s54, 6
	s_lshl_b32 s54, s54, 14
	v_and_b32_e32 v222, 63, v137
	v_and_b32_e32 v246, 15, v222
	v_lshrrev_b32_e32 v247, 4, v222
	v_and_b32_e32 v248, 3, v246
	v_xor_b32_e32 v248, v248, v247
	v_lshlrev_b32_e32 v248, 4, v248
	v_lshl_add_u32 v248, v246, 8, v248
	v_add_u32_e32 v248, s54, v248
	v_lshl_add_u32 v249, v222, 4, s54
	v_add_u32_e32 v250, s50, v247
	v_lshlrev_b32_e32 v250, 12, v250
	v_xor_b32_e32 v251, v246, v247
	v_lshl_add_u32 v250, v251, 4, v250
	s_lshl_b32 s55, s51, 2
	v_add_u32_e32 v250, s55, v250
	v_sub_f32_e32 v62, v62, v210
	v_sub_f32_e32 v63, v63, v210
	v_sub_f32_e32 v64, v64, v210
	v_sub_f32_e32 v65, v65, v210
	v_mul_f32_e32 v62, v214, v62
	v_mul_f32_e32 v63, v214, v63
	v_mul_f32_e32 v64, v214, v64
	v_mul_f32_e32 v65, v214, v65
	v_fma_f32 v62, v66, v62, v90
	v_fma_f32 v63, v67, v63, v91
	v_fma_f32 v64, v68, v64, v92
	v_fma_f32 v65, v69, v65, v93
	ds_write_b128 v248, v[62:65] offset:0
	v_sub_f32_e32 v86, v86, v210
	v_sub_f32_e32 v87, v87, v210
	v_sub_f32_e32 v88, v88, v210
	v_sub_f32_e32 v89, v89, v210
	v_mul_f32_e32 v86, v214, v86
	v_mul_f32_e32 v87, v214, v87
	v_mul_f32_e32 v88, v214, v88
	v_mul_f32_e32 v89, v214, v89
	v_fma_f32 v86, v74, v86, v94
	v_fma_f32 v87, v75, v87, v95
	v_fma_f32 v88, v76, v88, v96
	v_fma_f32 v89, v77, v89, v97
	ds_write_b128 v248, v[86:89] offset:64
	v_sub_f32_e32 v70, v70, v210
	v_sub_f32_e32 v71, v71, v210
	v_sub_f32_e32 v72, v72, v210
	v_sub_f32_e32 v73, v73, v210
	v_mul_f32_e32 v70, v214, v70
	v_mul_f32_e32 v71, v214, v71
	v_mul_f32_e32 v72, v214, v72
	v_mul_f32_e32 v73, v214, v73
	v_fma_f32 v70, v78, v70, v108
	v_fma_f32 v71, v79, v71, v109
	v_fma_f32 v72, v80, v72, v110
	v_fma_f32 v73, v81, v73, v111
	ds_write_b128 v248, v[70:73] offset:128
	v_sub_f32_e32 v176, v176, v210
	v_sub_f32_e32 v177, v177, v210
	v_sub_f32_e32 v178, v178, v210
	v_sub_f32_e32 v179, v179, v210
	v_mul_f32_e32 v176, v214, v176
	v_mul_f32_e32 v177, v214, v177
	v_mul_f32_e32 v178, v214, v178
	v_mul_f32_e32 v179, v214, v179
	v_fma_f32 v176, v82, v176, v172
	v_fma_f32 v177, v83, v177, v173
	v_fma_f32 v178, v84, v178, v174
	v_fma_f32 v179, v85, v179, v175
	ds_write_b128 v248, v[176:179] offset:192
	v_sub_f32_e32 v202, v202, v211
	v_sub_f32_e32 v203, v203, v211
	v_sub_f32_e32 v204, v204, v211
	v_sub_f32_e32 v205, v205, v211
	v_mul_f32_e32 v202, v215, v202
	v_mul_f32_e32 v203, v215, v203
	v_mul_f32_e32 v204, v215, v204
	v_mul_f32_e32 v205, v215, v205
	v_fma_f32 v202, v66, v202, v90
	v_fma_f32 v203, v67, v203, v91
	v_fma_f32 v204, v68, v204, v92
	v_fma_f32 v205, v69, v205, v93
	ds_write_b128 v248, v[202:205] offset:4096
	v_sub_f32_e32 v54, v54, v211
	v_sub_f32_e32 v55, v55, v211
	v_sub_f32_e32 v56, v56, v211
	v_sub_f32_e32 v57, v57, v211
	v_mul_f32_e32 v54, v215, v54
	v_mul_f32_e32 v55, v215, v55
	v_mul_f32_e32 v56, v215, v56
	v_mul_f32_e32 v57, v215, v57
	v_fma_f32 v54, v74, v54, v94
	v_fma_f32 v55, v75, v55, v95
	v_fma_f32 v56, v76, v56, v96
	v_fma_f32 v57, v77, v57, v97
	ds_write_b128 v248, v[54:57] offset:4160
	v_sub_f32_e32 v58, v58, v211
	v_sub_f32_e32 v59, v59, v211
	v_sub_f32_e32 v60, v60, v211
	v_sub_f32_e32 v61, v61, v211
	v_mul_f32_e32 v58, v215, v58
	v_mul_f32_e32 v59, v215, v59
	v_mul_f32_e32 v60, v215, v60
	v_mul_f32_e32 v61, v215, v61
	v_fma_f32 v58, v78, v58, v108
	v_fma_f32 v59, v79, v59, v109
	v_fma_f32 v60, v80, v60, v110
	v_fma_f32 v61, v81, v61, v111
	ds_write_b128 v248, v[58:61] offset:4224
	v_sub_f32_e32 v34, v34, v211
	v_sub_f32_e32 v35, v35, v211
	v_sub_f32_e32 v36, v36, v211
	v_sub_f32_e32 v37, v37, v211
	v_mul_f32_e32 v34, v215, v34
	v_mul_f32_e32 v35, v215, v35
	v_mul_f32_e32 v36, v215, v36
	v_mul_f32_e32 v37, v215, v37
	v_fma_f32 v34, v82, v34, v172
	v_fma_f32 v35, v83, v35, v173
	v_fma_f32 v36, v84, v36, v174
	v_fma_f32 v37, v85, v37, v175
	ds_write_b128 v248, v[34:37] offset:4288
	v_sub_f32_e32 v30, v30, v212
	v_sub_f32_e32 v31, v31, v212
	v_sub_f32_e32 v32, v32, v212
	v_sub_f32_e32 v33, v33, v212
	v_mul_f32_e32 v30, v216, v30
	v_mul_f32_e32 v31, v216, v31
	v_mul_f32_e32 v32, v216, v32
	v_mul_f32_e32 v33, v216, v33
	v_fma_f32 v30, v66, v30, v90
	v_fma_f32 v31, v67, v31, v91
	v_fma_f32 v32, v68, v32, v92
	v_fma_f32 v33, v69, v33, v93
	ds_write_b128 v248, v[30:33] offset:8192
	v_sub_f32_e32 v26, v26, v212
	v_sub_f32_e32 v27, v27, v212
	v_sub_f32_e32 v28, v28, v212
	v_sub_f32_e32 v29, v29, v212
	v_mul_f32_e32 v26, v216, v26
	v_mul_f32_e32 v27, v216, v27
	v_mul_f32_e32 v28, v216, v28
	v_mul_f32_e32 v29, v216, v29
	v_fma_f32 v26, v74, v26, v94
	v_fma_f32 v27, v75, v27, v95
	v_fma_f32 v28, v76, v28, v96
	v_fma_f32 v29, v77, v29, v97
	ds_write_b128 v248, v[26:29] offset:8256
	v_sub_f32_e32 v22, v22, v212
	v_sub_f32_e32 v23, v23, v212
	v_sub_f32_e32 v24, v24, v212
	v_sub_f32_e32 v25, v25, v212
	v_mul_f32_e32 v22, v216, v22
	v_mul_f32_e32 v23, v216, v23
	v_mul_f32_e32 v24, v216, v24
	v_mul_f32_e32 v25, v216, v25
	v_fma_f32 v22, v78, v22, v108
	v_fma_f32 v23, v79, v23, v109
	v_fma_f32 v24, v80, v24, v110
	v_fma_f32 v25, v81, v25, v111
	ds_write_b128 v248, v[22:25] offset:8320
	v_sub_f32_e32 v18, v18, v212
	v_sub_f32_e32 v19, v19, v212
	v_sub_f32_e32 v20, v20, v212
	v_sub_f32_e32 v21, v21, v212
	v_mul_f32_e32 v18, v216, v18
	v_mul_f32_e32 v19, v216, v19
	v_mul_f32_e32 v20, v216, v20
	v_mul_f32_e32 v21, v216, v21
	v_fma_f32 v18, v82, v18, v172
	v_fma_f32 v19, v83, v19, v173
	v_fma_f32 v20, v84, v20, v174
	v_fma_f32 v21, v85, v21, v175
	ds_write_b128 v248, v[18:21] offset:8384
	v_sub_f32_e32 v14, v14, v213
	v_sub_f32_e32 v15, v15, v213
	v_sub_f32_e32 v16, v16, v213
	v_sub_f32_e32 v17, v17, v213
	v_mul_f32_e32 v14, v217, v14
	v_mul_f32_e32 v15, v217, v15
	v_mul_f32_e32 v16, v217, v16
	v_mul_f32_e32 v17, v217, v17
	v_fma_f32 v14, v66, v14, v90
	v_fma_f32 v15, v67, v15, v91
	v_fma_f32 v16, v68, v16, v92
	v_fma_f32 v17, v69, v17, v93
	ds_write_b128 v248, v[14:17] offset:12288
	v_sub_f32_e32 v10, v10, v213
	v_sub_f32_e32 v11, v11, v213
	v_sub_f32_e32 v12, v12, v213
	v_sub_f32_e32 v13, v13, v213
	v_mul_f32_e32 v10, v217, v10
	v_mul_f32_e32 v11, v217, v11
	v_mul_f32_e32 v12, v217, v12
	v_mul_f32_e32 v13, v217, v13
	v_fma_f32 v10, v74, v10, v94
	v_fma_f32 v11, v75, v11, v95
	v_fma_f32 v12, v76, v12, v96
	v_fma_f32 v13, v77, v13, v97
	ds_write_b128 v248, v[10:13] offset:12352
	v_sub_f32_e32 v6, v6, v213
	v_sub_f32_e32 v7, v7, v213
	v_sub_f32_e32 v8, v8, v213
	v_sub_f32_e32 v9, v9, v213
	v_mul_f32_e32 v6, v217, v6
	v_mul_f32_e32 v7, v217, v7
	v_mul_f32_e32 v8, v217, v8
	v_mul_f32_e32 v9, v217, v9
	v_fma_f32 v6, v78, v6, v108
	v_fma_f32 v7, v79, v7, v109
	v_fma_f32 v8, v80, v8, v110
	v_fma_f32 v9, v81, v9, v111
	ds_write_b128 v248, v[6:9] offset:12416
	v_sub_f32_e32 v2, v2, v213
	v_sub_f32_e32 v3, v3, v213
	v_sub_f32_e32 v4, v4, v213
	v_sub_f32_e32 v5, v5, v213
	v_mul_f32_e32 v2, v217, v2
	v_mul_f32_e32 v3, v217, v3
	v_mul_f32_e32 v4, v217, v4
	v_mul_f32_e32 v5, v217, v5
	v_fma_f32 v2, v82, v2, v172
	v_fma_f32 v3, v83, v3, v173
	v_fma_f32 v4, v84, v4, v174
	v_fma_f32 v5, v85, v5, v175
	ds_write_b128 v248, v[2:5] offset:12480
	s_waitcnt lgkmcnt(0)
	ds_read_b128 v[66:69], v249 offset:0
	ds_read_b128 v[74:77], v249 offset:1024
	ds_read_b128 v[78:81], v249 offset:2048
	ds_read_b128 v[82:85], v249 offset:3072
	ds_read_b128 v[90:93], v249 offset:4096
	ds_read_b128 v[94:97], v249 offset:5120
	ds_read_b128 v[108:111], v249 offset:6144
	ds_read_b128 v[172:175], v249 offset:7168
	s_waitcnt lgkmcnt(7)
	global_store_dwordx4 v250, v[66:69], s[26:27] sc1
	s_waitcnt lgkmcnt(6)
	v_add_u32_e32 v251, 0x4000, v250
	global_store_dwordx4 v251, v[74:77], s[26:27] sc1
	s_waitcnt lgkmcnt(5)
	v_add_u32_e32 v251, 0x8000, v250
	global_store_dwordx4 v251, v[78:81], s[26:27] sc1
	s_waitcnt lgkmcnt(4)
	v_add_u32_e32 v251, 0xc000, v250
	global_store_dwordx4 v251, v[82:85], s[26:27] sc1
	s_waitcnt lgkmcnt(3)
	v_add_u32_e32 v251, 0x10000, v250
	global_store_dwordx4 v251, v[90:93], s[26:27] sc1
	s_waitcnt lgkmcnt(2)
	v_add_u32_e32 v251, 0x14000, v250
	global_store_dwordx4 v251, v[94:97], s[26:27] sc1
	s_waitcnt lgkmcnt(1)
	v_add_u32_e32 v251, 0x18000, v250
	global_store_dwordx4 v251, v[108:111], s[26:27] sc1
	s_waitcnt lgkmcnt(0)
	v_add_u32_e32 v251, 0x1c000, v250
	global_store_dwordx4 v251, v[172:175], s[26:27] sc1
	s_nop 1
	ds_read_b128 v[66:69], v249 offset:8192
	ds_read_b128 v[74:77], v249 offset:9216
	ds_read_b128 v[78:81], v249 offset:10240
	ds_read_b128 v[82:85], v249 offset:11264
	ds_read_b128 v[90:93], v249 offset:12288
	ds_read_b128 v[94:97], v249 offset:13312
	ds_read_b128 v[108:111], v249 offset:14336
	ds_read_b128 v[172:175], v249 offset:15360
	s_waitcnt lgkmcnt(7)
	v_add_u32_e32 v251, 0x20000, v250
	global_store_dwordx4 v251, v[66:69], s[26:27] sc1
	s_waitcnt lgkmcnt(6)
	v_add_u32_e32 v251, 0x24000, v250
	global_store_dwordx4 v251, v[74:77], s[26:27] sc1
	s_waitcnt lgkmcnt(5)
	v_add_u32_e32 v251, 0x28000, v250
	global_store_dwordx4 v251, v[78:81], s[26:27] sc1
	s_waitcnt lgkmcnt(4)
	v_add_u32_e32 v251, 0x2c000, v250
	global_store_dwordx4 v251, v[82:85], s[26:27] sc1
	s_waitcnt lgkmcnt(3)
	v_add_u32_e32 v251, 0x30000, v250
	global_store_dwordx4 v251, v[90:93], s[26:27] sc1
	s_waitcnt lgkmcnt(2)
	v_add_u32_e32 v251, 0x34000, v250
	global_store_dwordx4 v251, v[94:97], s[26:27] sc1
	s_waitcnt lgkmcnt(1)
	v_add_u32_e32 v251, 0x38000, v250
	global_store_dwordx4 v251, v[108:111], s[26:27] sc1
	s_waitcnt lgkmcnt(0)
	v_add_u32_e32 v251, 0x3c000, v250
	global_store_dwordx4 v251, v[172:175], s[26:27] sc1
	s_nop 1
	s_cmp_eq_u32 s53, 3
	s_cbranch_scc1 .Lln2_end
	s_add_u32 s34, s94, 0x7b48000
	s_addc_u32 s35, s95, 0
	s_waitcnt vmcnt(16)
	v_add_f32_e32 v226, 1.0, v226
	v_add_f32_e32 v227, 1.0, v227
	v_add_f32_e32 v228, 1.0, v228
	v_add_f32_e32 v229, 1.0, v229
	v_add_f32_e32 v230, 1.0, v230
	v_add_f32_e32 v231, 1.0, v231
	v_add_f32_e32 v232, 1.0, v232
	v_add_f32_e32 v233, 1.0, v233
	v_add_f32_e32 v234, 1.0, v234
	v_add_f32_e32 v235, 1.0, v235
	v_add_f32_e32 v236, 1.0, v236
	v_add_f32_e32 v237, 1.0, v237
	v_add_f32_e32 v238, 1.0, v238
	v_add_f32_e32 v239, 1.0, v239
	v_add_f32_e32 v240, 1.0, v240
	v_add_f32_e32 v241, 1.0, v241
	v_and_b32_e32 v251, 7, v246
	v_lshlrev_b32_e32 v251, 1, v251
	v_or_b32_e32 v218, 0, v247
	v_xor_b32_e32 v218, v218, v251
	v_lshlrev_b32_e32 v218, 3, v218
	v_lshl_add_u32 v218, v246, 7, v218
	v_add_u32_e32 v218, s54, v218
	v_or_b32_e32 v219, 4, v247
	v_xor_b32_e32 v219, v219, v251
	v_lshlrev_b32_e32 v219, 3, v219
	v_lshl_add_u32 v219, v246, 7, v219
	v_add_u32_e32 v219, s54, v219
	v_or_b32_e32 v220, 8, v247
	v_xor_b32_e32 v220, v220, v251
	v_lshlrev_b32_e32 v220, 3, v220
	v_lshl_add_u32 v220, v246, 7, v220
	v_add_u32_e32 v220, s54, v220
	v_or_b32_e32 v221, 12, v247
	v_xor_b32_e32 v221, v221, v251
	v_lshlrev_b32_e32 v221, 3, v221
	v_lshl_add_u32 v221, v246, 7, v221
	v_add_u32_e32 v221, s54, v221
	v_lshrrev_b32_e32 v248, 3, v222
	v_and_b32_e32 v251, 7, v222
	v_xor_b32_e32 v251, v251, v248
	v_add_u32_e32 v248, s50, v248
	v_lshlrev_b32_e32 v248, 11, v248
	v_lshl_add_u32 v248, v251, 4, v248
	s_lshl_b32 s55, s51, 1
	v_add_u32_e32 v248, s55, v248
	v_fma_f32 v62, v226, v62, v38
	v_fma_f32 v63, v227, v63, v39
	v_fma_f32 v64, v228, v64, v40
	v_fma_f32 v65, v229, v65, v41
	v_cvt_pk_bf16_f32 v62, v62, v63
	v_cvt_pk_bf16_f32 v63, v64, v65
	ds_write_b64 v218, v[62:63] offset:0
	v_fma_f32 v86, v230, v86, v42
	v_fma_f32 v87, v231, v87, v43
	v_fma_f32 v88, v232, v88, v44
	v_fma_f32 v89, v233, v89, v45
	v_cvt_pk_bf16_f32 v86, v86, v87
	v_cvt_pk_bf16_f32 v87, v88, v89
	ds_write_b64 v219, v[86:87] offset:0
	v_fma_f32 v70, v234, v70, v46
	v_fma_f32 v71, v235, v71, v47
	v_fma_f32 v72, v236, v72, v48
	v_fma_f32 v73, v237, v73, v49
	v_cvt_pk_bf16_f32 v70, v70, v71
	v_cvt_pk_bf16_f32 v71, v72, v73
	ds_write_b64 v220, v[70:71] offset:0
	v_fma_f32 v176, v238, v176, v50
	v_fma_f32 v177, v239, v177, v51
	v_fma_f32 v178, v240, v178, v52
	v_fma_f32 v179, v241, v179, v53
	v_cvt_pk_bf16_f32 v176, v176, v177
	v_cvt_pk_bf16_f32 v177, v178, v179
	ds_write_b64 v221, v[176:177] offset:0
	v_fma_f32 v202, v226, v202, v38
	v_fma_f32 v203, v227, v203, v39
	v_fma_f32 v204, v228, v204, v40
	v_fma_f32 v205, v229, v205, v41
	v_cvt_pk_bf16_f32 v202, v202, v203
	v_cvt_pk_bf16_f32 v203, v204, v205
	ds_write_b64 v218, v[202:203] offset:2048
	v_fma_f32 v54, v230, v54, v42
	v_fma_f32 v55, v231, v55, v43
	v_fma_f32 v56, v232, v56, v44
	v_fma_f32 v57, v233, v57, v45
	v_cvt_pk_bf16_f32 v54, v54, v55
	v_cvt_pk_bf16_f32 v55, v56, v57
	ds_write_b64 v219, v[54:55] offset:2048
	v_fma_f32 v58, v234, v58, v46
	v_fma_f32 v59, v235, v59, v47
	v_fma_f32 v60, v236, v60, v48
	v_fma_f32 v61, v237, v61, v49
	v_cvt_pk_bf16_f32 v58, v58, v59
	v_cvt_pk_bf16_f32 v59, v60, v61
	ds_write_b64 v220, v[58:59] offset:2048
	v_fma_f32 v34, v238, v34, v50
	v_fma_f32 v35, v239, v35, v51
	v_fma_f32 v36, v240, v36, v52
	v_fma_f32 v37, v241, v37, v53
	v_cvt_pk_bf16_f32 v34, v34, v35
	v_cvt_pk_bf16_f32 v35, v36, v37
	ds_write_b64 v221, v[34:35] offset:2048
	v_fma_f32 v30, v226, v30, v38
	v_fma_f32 v31, v227, v31, v39
	v_fma_f32 v32, v228, v32, v40
	v_fma_f32 v33, v229, v33, v41
	v_cvt_pk_bf16_f32 v30, v30, v31
	v_cvt_pk_bf16_f32 v31, v32, v33
	ds_write_b64 v218, v[30:31] offset:4096
	v_fma_f32 v26, v230, v26, v42
	v_fma_f32 v27, v231, v27, v43
	v_fma_f32 v28, v232, v28, v44
	v_fma_f32 v29, v233, v29, v45
	v_cvt_pk_bf16_f32 v26, v26, v27
	v_cvt_pk_bf16_f32 v27, v28, v29
	ds_write_b64 v219, v[26:27] offset:4096
	v_fma_f32 v22, v234, v22, v46
	v_fma_f32 v23, v235, v23, v47
	v_fma_f32 v24, v236, v24, v48
	v_fma_f32 v25, v237, v25, v49
	v_cvt_pk_bf16_f32 v22, v22, v23
	v_cvt_pk_bf16_f32 v23, v24, v25
	ds_write_b64 v220, v[22:23] offset:4096
	v_fma_f32 v18, v238, v18, v50
	v_fma_f32 v19, v239, v19, v51
	v_fma_f32 v20, v240, v20, v52
	v_fma_f32 v21, v241, v21, v53
	v_cvt_pk_bf16_f32 v18, v18, v19
	v_cvt_pk_bf16_f32 v19, v20, v21
	ds_write_b64 v221, v[18:19] offset:4096
	v_fma_f32 v14, v226, v14, v38
	v_fma_f32 v15, v227, v15, v39
	v_fma_f32 v16, v228, v16, v40
	v_fma_f32 v17, v229, v17, v41
	v_cvt_pk_bf16_f32 v14, v14, v15
	v_cvt_pk_bf16_f32 v15, v16, v17
	ds_write_b64 v218, v[14:15] offset:6144
	v_fma_f32 v10, v230, v10, v42
	v_fma_f32 v11, v231, v11, v43
	v_fma_f32 v12, v232, v12, v44
	v_fma_f32 v13, v233, v13, v45
	v_cvt_pk_bf16_f32 v10, v10, v11
	v_cvt_pk_bf16_f32 v11, v12, v13
	ds_write_b64 v219, v[10:11] offset:6144
	v_fma_f32 v6, v234, v6, v46
	v_fma_f32 v7, v235, v7, v47
	v_fma_f32 v8, v236, v8, v48
	v_fma_f32 v9, v237, v9, v49
	v_cvt_pk_bf16_f32 v6, v6, v7
	v_cvt_pk_bf16_f32 v7, v8, v9
	ds_write_b64 v220, v[6:7] offset:6144
	v_fma_f32 v2, v238, v2, v50
	v_fma_f32 v3, v239, v3, v51
	v_fma_f32 v4, v240, v4, v52
	v_fma_f32 v5, v241, v5, v53
	v_cvt_pk_bf16_f32 v2, v2, v3
	v_cvt_pk_bf16_f32 v3, v4, v5
	ds_write_b64 v221, v[2:3] offset:6144
	s_waitcnt lgkmcnt(0)
	ds_read_b128 v[66:69], v249 offset:0
	ds_read_b128 v[74:77], v249 offset:1024
	ds_read_b128 v[78:81], v249 offset:2048
	ds_read_b128 v[82:85], v249 offset:3072
	ds_read_b128 v[90:93], v249 offset:4096
	ds_read_b128 v[94:97], v249 offset:5120
	ds_read_b128 v[108:111], v249 offset:6144
	ds_read_b128 v[172:175], v249 offset:7168
	s_waitcnt lgkmcnt(7)
	global_store_dwordx4 v248, v[66:69], s[34:35] sc1
	s_waitcnt lgkmcnt(6)
	v_add_u32_e32 v251, 0x4000, v248
	global_store_dwordx4 v251, v[74:77], s[34:35] sc1
	s_waitcnt lgkmcnt(5)
	v_add_u32_e32 v251, 0x8000, v248
	global_store_dwordx4 v251, v[78:81], s[34:35] sc1
	s_waitcnt lgkmcnt(4)
	v_add_u32_e32 v251, 0xc000, v248
	global_store_dwordx4 v251, v[82:85], s[34:35] sc1
	s_waitcnt lgkmcnt(3)
	v_add_u32_e32 v251, 0x10000, v248
	global_store_dwordx4 v251, v[90:93], s[34:35] sc1
	s_waitcnt lgkmcnt(2)
	v_add_u32_e32 v251, 0x14000, v248
	global_store_dwordx4 v251, v[94:97], s[34:35] sc1
	s_waitcnt lgkmcnt(1)
	v_add_u32_e32 v251, 0x18000, v248
	global_store_dwordx4 v251, v[108:111], s[34:35] sc1
	s_waitcnt lgkmcnt(0)
	v_add_u32_e32 v251, 0x1c000, v248
	global_store_dwordx4 v251, v[172:175], s[34:35] sc1
